# MoBA loop: fully masked diagonal wave-tiles skipped (wave-uniform regimes in the near-tile path: no QK / PV only / nothing), on top of the no-flip GEMM
# speedup vs baseline: 1.0075x; 1.0061x over previous
.Lmb1_skVAn:
.Lmb1_A_g0near:
	s_lshr_b32 s45, s3, 1
	s_add_i32 s45, s45, s31
	s_add_i32 s45, s45, 3
	s_sub_i32 s45, s34, s45
	s_cmp_gt_i32 s45, 0
	s_cbranch_scc1 .Lmb1_A_tail
	s_waitcnt lgkmcnt(8)
	v_mfma_f32_32x32x16_bf16 v[16:31], v[108:111], v[186:189], v[16:31]
	v_mfma_f32_32x32x16_bf16 v[16:31], v[104:107], v[190:193], v[16:31]
	v_mfma_f32_32x32x16_bf16 v[16:31], v[100:103], v[194:197], v[16:31]
	v_mfma_f32_32x32x16_bf16 v[16:31], v[96:99], v[198:201], v[16:31]
	v_mfma_f32_32x32x16_bf16 v[32:47], v[108:111], v[202:205], v[32:47]
	v_mfma_f32_32x32x16_bf16 v[32:47], v[104:107], v[206:209], v[32:47]
	v_mfma_f32_32x32x16_bf16 v[32:47], v[100:103], v[210:213], v[32:47]
	v_mfma_f32_32x32x16_bf16 v[32:47], v[96:99], v[214:217], v[32:47]
	s_cmp_eq_u32 s45, 0
	s_cbranch_scc1 .Lmb1_A_zpw
	s_cmp_eq_i32 s45, -1
	s_cbranch_scc1 .Lmb1_A_noqk
	s_lshr_b32 s44, s34, 2
	s_cmp_eq_u32 s44, s91
	s_cselect_b64 s[8:9], -1, 0
	s_lshl_b32 s44, 1, s44
	v_and_b32_e32 v96, s44, v129
	v_cmp_ne_u32_e32 vcc, 0, v96
	s_or_b64 vcc, s[8:9], vcc
	s_nop 0
	v_cndmask_b32_e32 v96, v127, v112, vcc
	v_lshl_add_u32 v96, v96, 2, 0
	v_add_u32_e32 v104, 0x1d000, v96
	ds_read2_b32 v[96:97], v104 offset0:58 offset1:59
	ds_read2_b32 v[98:99], v104 offset0:26 offset1:27
	ds_read2_b32 v[100:101], v104 offset0:56 offset1:57
	s_waitcnt lgkmcnt(2)
	v_pk_add_f32 v[64:65], v[64:65], v[96:97] op_sel:[0,1] op_sel_hi:[1,0]
	ds_read2_b32 v[96:97], v104 offset0:24 offset1:25
	s_waitcnt lgkmcnt(2)
	v_pk_add_f32 v[48:49], v[48:49], v[98:99] op_sel:[0,1] op_sel_hi:[1,0]
	ds_read2_b32 v[98:99], v104 offset0:50 offset1:51
	s_waitcnt lgkmcnt(2)
	v_pk_add_f32 v[66:67], v[66:67], v[100:101] op_sel:[0,1] op_sel_hi:[1,0]
	ds_read2_b32 v[100:101], v104 offset0:18 offset1:19
	s_waitcnt lgkmcnt(1)
	v_pk_add_f32 v[68:69], v[68:69], v[98:99] op_sel:[0,1] op_sel_hi:[1,0]
	ds_read2_b32 v[98:99], v104 offset0:16 offset1:17
	s_waitcnt lgkmcnt(1)
	v_pk_add_f32 v[52:53], v[52:53], v[100:101] op_sel:[0,1] op_sel_hi:[1,0]
	ds_read2_b32 v[100:101], v104 offset0:42 offset1:43
	v_pk_add_f32 v[50:51], v[50:51], v[96:97] op_sel:[0,1] op_sel_hi:[1,0]
	ds_read2_b32 v[96:97], v104 offset0:48 offset1:49
	s_waitcnt lgkmcnt(1)
	v_pk_add_f32 v[72:73], v[72:73], v[100:101] op_sel:[0,1] op_sel_hi:[1,0]
	ds_read2_b32 v[100:101], v104 offset0:8 offset1:9
	s_waitcnt lgkmcnt(1)
	v_pk_add_f32 v[70:71], v[70:71], v[96:97] op_sel:[0,1] op_sel_hi:[1,0]
	ds_read2_b32 v[96:97], v104 offset0:10 offset1:11
	v_pk_add_f32 v[54:55], v[54:55], v[98:99] op_sel:[0,1] op_sel_hi:[1,0]
	ds_read2_b32 v[98:99], v104 offset0:40 offset1:41
	s_waitcnt lgkmcnt(2)
	v_pk_add_f32 v[58:59], v[58:59], v[100:101] op_sel:[0,1] op_sel_hi:[1,0]
	s_waitcnt lgkmcnt(1)
	v_pk_add_f32 v[56:57], v[56:57], v[96:97] op_sel:[0,1] op_sel_hi:[1,0]
	ds_read2_b32 v[96:97], v104 offset0:34 offset1:35
	s_waitcnt lgkmcnt(1)
	v_pk_add_f32 v[74:75], v[74:75], v[98:99] op_sel:[0,1] op_sel_hi:[1,0]
	ds_read2_b32 v[98:99], v104 offset0:2 offset1:3
	ds_read2_b32 v[102:103], v104 offset0:32 offset1:33
	ds_read2_b32 v[104:105], v104 offset1:1
	s_waitcnt lgkmcnt(3)
	v_pk_add_f32 v[76:77], v[76:77], v[96:97] op_sel:[0,1] op_sel_hi:[1,0]
	s_waitcnt lgkmcnt(2)
	v_pk_add_f32 v[60:61], v[60:61], v[98:99] op_sel:[0,1] op_sel_hi:[1,0]
	s_waitcnt lgkmcnt(1)
	v_pk_add_f32 v[78:79], v[78:79], v[102:103] op_sel:[0,1] op_sel_hi:[1,0]
	s_waitcnt lgkmcnt(0)
	v_pk_add_f32 v[62:63], v[62:63], v[104:105] op_sel:[0,1] op_sel_hi:[1,0]
	s_waitcnt lgkmcnt(0)
	v_mfma_f32_32x32x16_bf16 v[236:251], v[154:157], v[92:95], v[220:235]
	ds_read_b64_tr_b16 v[186:187], v218
	ds_read_b64_tr_b16 v[188:189], v218 offset:512
	ds_read_b64_tr_b16 v[190:191], v218 offset:1024
	ds_read_b64_tr_b16 v[192:193], v218 offset:1536
	ds_read_b64_tr_b16 v[194:195], v218 offset:2048
	ds_read_b64_tr_b16 v[196:197], v218 offset:2560
	ds_read_b64_tr_b16 v[198:199], v218 offset:3072
	ds_read_b64_tr_b16 v[200:201], v218 offset:3584
	ds_read_b64_tr_b16 v[202:203], v218 offset:4096
	ds_read_b64_tr_b16 v[204:205], v218 offset:4608
	ds_read_b64_tr_b16 v[206:207], v218 offset:5120
	v_mfma_f32_32x32x16_bf16 v[134:149], v[158:161], v[92:95], v[220:235]
	ds_read_b64_tr_b16 v[208:209], v218 offset:5632
	ds_read_b64_tr_b16 v[210:211], v218 offset:6144
	ds_read_b64_tr_b16 v[212:213], v218 offset:6656
	ds_read_b64_tr_b16 v[214:215], v218 offset:7168
	ds_read_b64_tr_b16 v[216:217], v218 offset:7680
	v_exp_f32_e32 v64, v64
	v_exp_f32_e32 v48, v48
	v_exp_f32_e32 v65, v65
	v_exp_f32_e32 v49, v49
	v_exp_f32_e32 v66, v66
	v_exp_f32_e32 v50, v50
	v_mfma_f32_32x32x16_bf16 v[236:251], v[162:165], v[88:91], v[236:251]
	v_exp_f32_e32 v67, v67
	v_exp_f32_e32 v51, v51
	v_add_f32_e32 v252, v48, v64
	v_exp_f32_e32 v68, v68
	v_exp_f32_e32 v52, v52
	v_add_f32_e32 v252, 0, v252
	v_add_f32_e32 v253, v49, v65
	v_exp_f32_e32 v69, v69
	v_exp_f32_e32 v53, v53
	v_add_f32_e32 v252, v253, v252
	v_add_f32_e32 v253, v50, v66
	v_mfma_f32_32x32x16_bf16 v[134:149], v[166:169], v[88:91], v[134:149]
	v_exp_f32_e32 v70, v70
	v_exp_f32_e32 v54, v54
	v_add_f32_e32 v252, v253, v252
	v_add_f32_e32 v253, v51, v67
	v_exp_f32_e32 v71, v71
	v_exp_f32_e32 v55, v55
	v_add_f32_e32 v252, v253, v252
	v_add_f32_e32 v253, v52, v68
	v_exp_f32_e32 v72, v72
	v_exp_f32_e32 v56, v56
	v_add_f32_e32 v252, v253, v252
	v_mfma_f32_32x32x16_bf16 v[236:251], v[170:173], v[84:87], v[236:251]
	v_add_f32_e32 v253, v53, v69
	v_exp_f32_e32 v73, v73
	v_exp_f32_e32 v57, v57
	v_add_f32_e32 v252, v253, v252
	v_add_f32_e32 v253, v54, v70
	v_exp_f32_e32 v74, v74
	v_exp_f32_e32 v58, v58
	v_add_f32_e32 v252, v253, v252
	v_add_f32_e32 v253, v55, v71
	v_exp_f32_e32 v75, v75
	v_exp_f32_e32 v59, v59
	v_mfma_f32_32x32x16_bf16 v[134:149], v[174:177], v[84:87], v[134:149]
	v_add_f32_e32 v252, v253, v252
	v_add_f32_e32 v253, v56, v72
	v_exp_f32_e32 v76, v76
	v_exp_f32_e32 v60, v60
	v_add_f32_e32 v252, v253, v252
	v_add_f32_e32 v253, v57, v73
	v_exp_f32_e32 v77, v77
	v_exp_f32_e32 v61, v61
	v_add_f32_e32 v252, v253, v252
	v_add_f32_e32 v253, v58, v74
	v_exp_f32_e32 v78, v78
	v_mfma_f32_32x32x16_bf16 v[236:251], v[178:181], v[80:83], v[236:251]
	v_exp_f32_e32 v62, v62
	v_add_f32_e32 v252, v253, v252
	v_add_f32_e32 v253, v59, v75
	v_exp_f32_e32 v79, v79
	v_exp_f32_e32 v63, v63
	v_add_f32_e32 v252, v253, v252
	v_add_f32_e32 v253, v60, v76
	v_add_f32_e32 v252, v253, v252
	v_add_f32_e32 v253, v61, v77
	v_add_f32_e32 v252, v253, v252
	v_add_f32_e32 v253, v62, v78
	v_mfma_f32_32x32x16_bf16 v[134:149], v[182:185], v[80:83], v[134:149]
	v_add_f32_e32 v252, v253, v252
	v_add_f32_e32 v253, v63, v79
	v_add_f32_e32 v252, v253, v252
	v_add_f32_e32 v131, v131, v252
	v_cvt_pk_bf16_f32 v108, v64, v65
	v_cvt_pk_bf16_f32 v109, v66, v67
	v_cvt_pk_bf16_f32 v110, v68, v69
	v_cvt_pk_bf16_f32 v111, v70, v71
	v_cvt_pk_bf16_f32 v104, v72, v73
	v_cvt_pk_bf16_f32 v105, v74, v75
	v_cvt_pk_bf16_f32 v106, v76, v77
	v_cvt_pk_bf16_f32 v107, v78, v79
	v_cvt_pk_bf16_f32 v100, v48, v49
	v_cvt_pk_bf16_f32 v101, v50, v51
	v_cvt_pk_bf16_f32 v102, v52, v53
	v_cvt_pk_bf16_f32 v103, v54, v55
	v_cvt_pk_bf16_f32 v96, v56, v57
	v_cvt_pk_bf16_f32 v97, v58, v59
	v_cvt_pk_bf16_f32 v98, v60, v61
	v_cvt_pk_bf16_f32 v99, v62, v63
	s_branch .Lmb1_A_tail
.Lmb1_A_noqk:
	s_lshr_b32 s44, s34, 2
	s_cmp_eq_u32 s44, s91
	s_cselect_b64 s[8:9], -1, 0
	s_lshl_b32 s44, 1, s44
	v_and_b32_e32 v96, s44, v129
	v_cmp_ne_u32_e32 vcc, 0, v96
	s_or_b64 vcc, s[8:9], vcc
	s_nop 0
	v_cndmask_b32_e32 v96, v127, v112, vcc
	v_lshl_add_u32 v96, v96, 2, 0
	v_add_u32_e32 v104, 0x1d000, v96
	ds_read2_b32 v[96:97], v104 offset0:58 offset1:59
	ds_read2_b32 v[98:99], v104 offset0:26 offset1:27
	ds_read2_b32 v[100:101], v104 offset0:56 offset1:57
	s_waitcnt lgkmcnt(2)
	v_pk_add_f32 v[64:65], v[64:65], v[96:97] op_sel:[0,1] op_sel_hi:[1,0]
	ds_read2_b32 v[96:97], v104 offset0:24 offset1:25
	s_waitcnt lgkmcnt(2)
	v_pk_add_f32 v[48:49], v[48:49], v[98:99] op_sel:[0,1] op_sel_hi:[1,0]
	ds_read2_b32 v[98:99], v104 offset0:50 offset1:51
	s_waitcnt lgkmcnt(2)
	v_pk_add_f32 v[66:67], v[66:67], v[100:101] op_sel:[0,1] op_sel_hi:[1,0]
	ds_read2_b32 v[100:101], v104 offset0:18 offset1:19
	s_waitcnt lgkmcnt(1)
	v_pk_add_f32 v[68:69], v[68:69], v[98:99] op_sel:[0,1] op_sel_hi:[1,0]
	ds_read2_b32 v[98:99], v104 offset0:16 offset1:17
	s_waitcnt lgkmcnt(1)
	v_pk_add_f32 v[52:53], v[52:53], v[100:101] op_sel:[0,1] op_sel_hi:[1,0]
	ds_read2_b32 v[100:101], v104 offset0:42 offset1:43
	v_pk_add_f32 v[50:51], v[50:51], v[96:97] op_sel:[0,1] op_sel_hi:[1,0]
	ds_read2_b32 v[96:97], v104 offset0:48 offset1:49
	s_waitcnt lgkmcnt(1)
	v_pk_add_f32 v[72:73], v[72:73], v[100:101] op_sel:[0,1] op_sel_hi:[1,0]
	ds_read2_b32 v[100:101], v104 offset0:8 offset1:9
	s_waitcnt lgkmcnt(1)
	v_pk_add_f32 v[70:71], v[70:71], v[96:97] op_sel:[0,1] op_sel_hi:[1,0]
	ds_read2_b32 v[96:97], v104 offset0:10 offset1:11
	v_pk_add_f32 v[54:55], v[54:55], v[98:99] op_sel:[0,1] op_sel_hi:[1,0]
	ds_read2_b32 v[98:99], v104 offset0:40 offset1:41
	s_waitcnt lgkmcnt(2)
	v_pk_add_f32 v[58:59], v[58:59], v[100:101] op_sel:[0,1] op_sel_hi:[1,0]
	s_waitcnt lgkmcnt(1)
	v_pk_add_f32 v[56:57], v[56:57], v[96:97] op_sel:[0,1] op_sel_hi:[1,0]
	ds_read2_b32 v[96:97], v104 offset0:34 offset1:35
	s_waitcnt lgkmcnt(1)
	v_pk_add_f32 v[74:75], v[74:75], v[98:99] op_sel:[0,1] op_sel_hi:[1,0]
	ds_read2_b32 v[98:99], v104 offset0:2 offset1:3
	ds_read2_b32 v[102:103], v104 offset0:32 offset1:33
	ds_read2_b32 v[104:105], v104 offset1:1
	s_waitcnt lgkmcnt(3)
	v_pk_add_f32 v[76:77], v[76:77], v[96:97] op_sel:[0,1] op_sel_hi:[1,0]
	s_waitcnt lgkmcnt(2)
	v_pk_add_f32 v[60:61], v[60:61], v[98:99] op_sel:[0,1] op_sel_hi:[1,0]
	s_waitcnt lgkmcnt(1)
	v_pk_add_f32 v[78:79], v[78:79], v[102:103] op_sel:[0,1] op_sel_hi:[1,0]
	s_waitcnt lgkmcnt(0)
	v_pk_add_f32 v[62:63], v[62:63], v[104:105] op_sel:[0,1] op_sel_hi:[1,0]
	s_waitcnt lgkmcnt(0)
	ds_read_b64_tr_b16 v[186:187], v218
	ds_read_b64_tr_b16 v[188:189], v218 offset:512
	ds_read_b64_tr_b16 v[190:191], v218 offset:1024
	ds_read_b64_tr_b16 v[192:193], v218 offset:1536
	ds_read_b64_tr_b16 v[194:195], v218 offset:2048
	ds_read_b64_tr_b16 v[196:197], v218 offset:2560
	ds_read_b64_tr_b16 v[198:199], v218 offset:3072
	ds_read_b64_tr_b16 v[200:201], v218 offset:3584
	ds_read_b64_tr_b16 v[202:203], v218 offset:4096
	ds_read_b64_tr_b16 v[204:205], v218 offset:4608
	ds_read_b64_tr_b16 v[206:207], v218 offset:5120
	ds_read_b64_tr_b16 v[208:209], v218 offset:5632
	ds_read_b64_tr_b16 v[210:211], v218 offset:6144
	ds_read_b64_tr_b16 v[212:213], v218 offset:6656
	ds_read_b64_tr_b16 v[214:215], v218 offset:7168
	ds_read_b64_tr_b16 v[216:217], v218 offset:7680
	v_exp_f32_e32 v64, v64
	v_exp_f32_e32 v48, v48
	v_exp_f32_e32 v65, v65
	v_exp_f32_e32 v49, v49
	v_exp_f32_e32 v66, v66
	v_exp_f32_e32 v50, v50
	v_exp_f32_e32 v67, v67
	v_exp_f32_e32 v51, v51
	v_add_f32_e32 v252, v48, v64
	v_exp_f32_e32 v68, v68
	v_exp_f32_e32 v52, v52
	v_add_f32_e32 v252, 0, v252
	v_add_f32_e32 v253, v49, v65
	v_exp_f32_e32 v69, v69
	v_exp_f32_e32 v53, v53
	v_add_f32_e32 v252, v253, v252
	v_add_f32_e32 v253, v50, v66
	v_exp_f32_e32 v70, v70
	v_exp_f32_e32 v54, v54
	v_add_f32_e32 v252, v253, v252
	v_add_f32_e32 v253, v51, v67
	v_exp_f32_e32 v71, v71
	v_exp_f32_e32 v55, v55
	v_add_f32_e32 v252, v253, v252
	v_add_f32_e32 v253, v52, v68
	v_exp_f32_e32 v72, v72
	v_exp_f32_e32 v56, v56
	v_add_f32_e32 v252, v253, v252
	v_add_f32_e32 v253, v53, v69
	v_exp_f32_e32 v73, v73
	v_exp_f32_e32 v57, v57
	v_add_f32_e32 v252, v253, v252
	v_add_f32_e32 v253, v54, v70
	v_exp_f32_e32 v74, v74
	v_exp_f32_e32 v58, v58
	v_add_f32_e32 v252, v253, v252
	v_add_f32_e32 v253, v55, v71
	v_exp_f32_e32 v75, v75
	v_exp_f32_e32 v59, v59
	v_add_f32_e32 v252, v253, v252
	v_add_f32_e32 v253, v56, v72
	v_exp_f32_e32 v76, v76
	v_exp_f32_e32 v60, v60
	v_add_f32_e32 v252, v253, v252
	v_add_f32_e32 v253, v57, v73
	v_exp_f32_e32 v77, v77
	v_exp_f32_e32 v61, v61
	v_add_f32_e32 v252, v253, v252
	v_add_f32_e32 v253, v58, v74
	v_exp_f32_e32 v78, v78
	v_exp_f32_e32 v62, v62
	v_add_f32_e32 v252, v253, v252
	v_add_f32_e32 v253, v59, v75
	v_exp_f32_e32 v79, v79
	v_exp_f32_e32 v63, v63
	v_add_f32_e32 v252, v253, v252
	v_add_f32_e32 v253, v60, v76
	v_add_f32_e32 v252, v253, v252
	v_add_f32_e32 v253, v61, v77
	v_add_f32_e32 v252, v253, v252
	v_add_f32_e32 v253, v62, v78
	v_add_f32_e32 v252, v253, v252
	v_add_f32_e32 v253, v63, v79
	v_add_f32_e32 v252, v253, v252
	v_add_f32_e32 v131, v131, v252
	v_cvt_pk_bf16_f32 v108, v64, v65
	v_cvt_pk_bf16_f32 v109, v66, v67
	v_cvt_pk_bf16_f32 v110, v68, v69
	v_cvt_pk_bf16_f32 v111, v70, v71
	v_cvt_pk_bf16_f32 v104, v72, v73
	v_cvt_pk_bf16_f32 v105, v74, v75
	v_cvt_pk_bf16_f32 v106, v76, v77
	v_cvt_pk_bf16_f32 v107, v78, v79
	v_cvt_pk_bf16_f32 v100, v48, v49
	v_cvt_pk_bf16_f32 v101, v50, v51
	v_cvt_pk_bf16_f32 v102, v52, v53
	v_cvt_pk_bf16_f32 v103, v54, v55
	v_cvt_pk_bf16_f32 v96, v56, v57
	v_cvt_pk_bf16_f32 v97, v58, v59
	v_cvt_pk_bf16_f32 v98, v60, v61
	v_cvt_pk_bf16_f32 v99, v62, v63
	s_branch .Lmb1_A_tail
.Lmb1_A_zpw:
	s_nop 7
	v_mov_b32_e32 v96, 0
	v_mov_b32_e32 v97, 0
	v_mov_b32_e32 v98, 0
	v_mov_b32_e32 v99, 0
	v_mov_b32_e32 v100, 0
	v_mov_b32_e32 v101, 0
	v_mov_b32_e32 v102, 0
	v_mov_b32_e32 v103, 0
	v_mov_b32_e32 v104, 0
	v_mov_b32_e32 v105, 0
	v_mov_b32_e32 v106, 0
	v_mov_b32_e32 v107, 0
	v_mov_b32_e32 v108, 0
	v_mov_b32_e32 v109, 0
	v_mov_b32_e32 v110, 0
	v_mov_b32_e32 v111, 0
	s_branch .Lmb1_A_tail

.Lmb1_skVBn:
.Lmb1_B_g0near:
	s_lshr_b32 s45, s3, 1
	s_add_i32 s45, s45, s31
	s_add_i32 s45, s45, 3
	s_sub_i32 s45, s34, s45
	s_cmp_gt_i32 s45, 0
	s_cbranch_scc1 .Lmb1_B_tail
	s_waitcnt lgkmcnt(8)
	v_mfma_f32_32x32x16_bf16 v[16:31], v[108:111], v[186:189], v[16:31]
	v_mfma_f32_32x32x16_bf16 v[16:31], v[104:107], v[190:193], v[16:31]
	v_mfma_f32_32x32x16_bf16 v[16:31], v[100:103], v[194:197], v[16:31]
	v_mfma_f32_32x32x16_bf16 v[16:31], v[96:99], v[198:201], v[16:31]
	v_mfma_f32_32x32x16_bf16 v[32:47], v[108:111], v[202:205], v[32:47]
	v_mfma_f32_32x32x16_bf16 v[32:47], v[104:107], v[206:209], v[32:47]
	v_mfma_f32_32x32x16_bf16 v[32:47], v[100:103], v[210:213], v[32:47]
	v_mfma_f32_32x32x16_bf16 v[32:47], v[96:99], v[214:217], v[32:47]
	s_cmp_eq_u32 s45, 0
	s_cbranch_scc1 .Lmb1_B_zpw
	s_cmp_eq_i32 s45, -1
	s_cbranch_scc1 .Lmb1_B_noqk
	s_lshr_b32 s44, s34, 2
	s_cmp_eq_u32 s44, s91
	s_cselect_b64 s[8:9], -1, 0
	s_lshl_b32 s44, 1, s44
	v_and_b32_e32 v96, s44, v129
	v_cmp_ne_u32_e32 vcc, 0, v96
	s_or_b64 vcc, s[8:9], vcc
	s_nop 0
	v_cndmask_b32_e32 v96, v127, v112, vcc
	v_lshl_add_u32 v96, v96, 2, 0
	v_add_u32_e32 v104, 0x1d000, v96
	ds_read2_b32 v[96:97], v104 offset0:58 offset1:59
	ds_read2_b32 v[98:99], v104 offset0:26 offset1:27
	ds_read2_b32 v[100:101], v104 offset0:56 offset1:57
	s_waitcnt lgkmcnt(2)
	v_pk_add_f32 v[236:237], v[236:237], v[96:97] op_sel:[0,1] op_sel_hi:[1,0]
	ds_read2_b32 v[96:97], v104 offset0:24 offset1:25
	s_waitcnt lgkmcnt(2)
	v_pk_add_f32 v[134:135], v[134:135], v[98:99] op_sel:[0,1] op_sel_hi:[1,0]
	ds_read2_b32 v[98:99], v104 offset0:50 offset1:51
	s_waitcnt lgkmcnt(2)
	v_pk_add_f32 v[238:239], v[238:239], v[100:101] op_sel:[0,1] op_sel_hi:[1,0]
	ds_read2_b32 v[100:101], v104 offset0:18 offset1:19
	s_waitcnt lgkmcnt(1)
	v_pk_add_f32 v[240:241], v[240:241], v[98:99] op_sel:[0,1] op_sel_hi:[1,0]
	ds_read2_b32 v[98:99], v104 offset0:16 offset1:17
	s_waitcnt lgkmcnt(1)
	v_pk_add_f32 v[138:139], v[138:139], v[100:101] op_sel:[0,1] op_sel_hi:[1,0]
	ds_read2_b32 v[100:101], v104 offset0:42 offset1:43
	v_pk_add_f32 v[136:137], v[136:137], v[96:97] op_sel:[0,1] op_sel_hi:[1,0]
	ds_read2_b32 v[96:97], v104 offset0:48 offset1:49
	s_waitcnt lgkmcnt(1)
	v_pk_add_f32 v[244:245], v[244:245], v[100:101] op_sel:[0,1] op_sel_hi:[1,0]
	ds_read2_b32 v[100:101], v104 offset0:8 offset1:9
	s_waitcnt lgkmcnt(1)
	v_pk_add_f32 v[242:243], v[242:243], v[96:97] op_sel:[0,1] op_sel_hi:[1,0]
	ds_read2_b32 v[96:97], v104 offset0:10 offset1:11
	v_pk_add_f32 v[140:141], v[140:141], v[98:99] op_sel:[0,1] op_sel_hi:[1,0]
	ds_read2_b32 v[98:99], v104 offset0:40 offset1:41
	s_waitcnt lgkmcnt(2)
	v_pk_add_f32 v[144:145], v[144:145], v[100:101] op_sel:[0,1] op_sel_hi:[1,0]
	s_waitcnt lgkmcnt(1)
	v_pk_add_f32 v[142:143], v[142:143], v[96:97] op_sel:[0,1] op_sel_hi:[1,0]
	ds_read2_b32 v[96:97], v104 offset0:34 offset1:35
	s_waitcnt lgkmcnt(1)
	v_pk_add_f32 v[246:247], v[246:247], v[98:99] op_sel:[0,1] op_sel_hi:[1,0]
	ds_read2_b32 v[98:99], v104 offset0:2 offset1:3
	ds_read2_b32 v[102:103], v104 offset0:32 offset1:33
	ds_read2_b32 v[104:105], v104 offset1:1
	s_waitcnt lgkmcnt(3)
	v_pk_add_f32 v[248:249], v[248:249], v[96:97] op_sel:[0,1] op_sel_hi:[1,0]
	s_waitcnt lgkmcnt(2)
	v_pk_add_f32 v[146:147], v[146:147], v[98:99] op_sel:[0,1] op_sel_hi:[1,0]
	s_waitcnt lgkmcnt(1)
	v_pk_add_f32 v[250:251], v[250:251], v[102:103] op_sel:[0,1] op_sel_hi:[1,0]
	s_waitcnt lgkmcnt(0)
	v_pk_add_f32 v[148:149], v[148:149], v[104:105] op_sel:[0,1] op_sel_hi:[1,0]
	s_waitcnt lgkmcnt(0)
	v_mfma_f32_32x32x16_bf16 v[64:79], v[154:157], v[92:95], v[220:235]
	ds_read_b64_tr_b16 v[186:187], v218
	ds_read_b64_tr_b16 v[188:189], v218 offset:512
	ds_read_b64_tr_b16 v[190:191], v218 offset:1024
	ds_read_b64_tr_b16 v[192:193], v218 offset:1536
	ds_read_b64_tr_b16 v[194:195], v218 offset:2048
	ds_read_b64_tr_b16 v[196:197], v218 offset:2560
	ds_read_b64_tr_b16 v[198:199], v218 offset:3072
	ds_read_b64_tr_b16 v[200:201], v218 offset:3584
	ds_read_b64_tr_b16 v[202:203], v218 offset:4096
	ds_read_b64_tr_b16 v[204:205], v218 offset:4608
	ds_read_b64_tr_b16 v[206:207], v218 offset:5120
	v_mfma_f32_32x32x16_bf16 v[48:63], v[158:161], v[92:95], v[220:235]
	ds_read_b64_tr_b16 v[208:209], v218 offset:5632
	ds_read_b64_tr_b16 v[210:211], v218 offset:6144
	ds_read_b64_tr_b16 v[212:213], v218 offset:6656
	ds_read_b64_tr_b16 v[214:215], v218 offset:7168
	ds_read_b64_tr_b16 v[216:217], v218 offset:7680
	v_exp_f32_e32 v236, v236
	v_exp_f32_e32 v134, v134
	v_exp_f32_e32 v237, v237
	v_exp_f32_e32 v135, v135
	v_exp_f32_e32 v238, v238
	v_exp_f32_e32 v136, v136
	v_mfma_f32_32x32x16_bf16 v[64:79], v[162:165], v[88:91], v[64:79]
	v_exp_f32_e32 v239, v239
	v_exp_f32_e32 v137, v137
	v_add_f32_e32 v252, v134, v236
	v_exp_f32_e32 v240, v240
	v_exp_f32_e32 v138, v138
	v_add_f32_e32 v252, 0, v252
	v_add_f32_e32 v253, v135, v237
	v_exp_f32_e32 v241, v241
	v_exp_f32_e32 v139, v139
	v_add_f32_e32 v252, v253, v252
	v_add_f32_e32 v253, v136, v238
	v_mfma_f32_32x32x16_bf16 v[48:63], v[166:169], v[88:91], v[48:63]
	v_exp_f32_e32 v242, v242
	v_exp_f32_e32 v140, v140
	v_add_f32_e32 v252, v253, v252
	v_add_f32_e32 v253, v137, v239
	v_exp_f32_e32 v243, v243
	v_exp_f32_e32 v141, v141
	v_add_f32_e32 v252, v253, v252
	v_add_f32_e32 v253, v138, v240
	v_exp_f32_e32 v244, v244
	v_exp_f32_e32 v142, v142
	v_add_f32_e32 v252, v253, v252
	v_mfma_f32_32x32x16_bf16 v[64:79], v[170:173], v[84:87], v[64:79]
	v_add_f32_e32 v253, v139, v241
	v_exp_f32_e32 v245, v245
	v_exp_f32_e32 v143, v143
	v_add_f32_e32 v252, v253, v252
	v_add_f32_e32 v253, v140, v242
	v_exp_f32_e32 v246, v246
	v_exp_f32_e32 v144, v144
	v_add_f32_e32 v252, v253, v252
	v_add_f32_e32 v253, v141, v243
	v_exp_f32_e32 v247, v247
	v_exp_f32_e32 v145, v145
	v_mfma_f32_32x32x16_bf16 v[48:63], v[174:177], v[84:87], v[48:63]
	v_add_f32_e32 v252, v253, v252
	v_add_f32_e32 v253, v142, v244
	v_exp_f32_e32 v248, v248
	v_exp_f32_e32 v146, v146
	v_add_f32_e32 v252, v253, v252
	v_add_f32_e32 v253, v143, v245
	v_exp_f32_e32 v249, v249
	v_exp_f32_e32 v147, v147
	v_add_f32_e32 v252, v253, v252
	v_add_f32_e32 v253, v144, v246
	v_exp_f32_e32 v250, v250
	v_mfma_f32_32x32x16_bf16 v[64:79], v[178:181], v[80:83], v[64:79]
	v_exp_f32_e32 v148, v148
	v_add_f32_e32 v252, v253, v252
	v_add_f32_e32 v253, v145, v247
	v_exp_f32_e32 v251, v251
	v_exp_f32_e32 v149, v149
	v_add_f32_e32 v252, v253, v252
	v_add_f32_e32 v253, v146, v248
	v_add_f32_e32 v252, v253, v252
	v_add_f32_e32 v253, v147, v249
	v_add_f32_e32 v252, v253, v252
	v_add_f32_e32 v253, v148, v250
	v_mfma_f32_32x32x16_bf16 v[48:63], v[182:185], v[80:83], v[48:63]
	v_add_f32_e32 v252, v253, v252
	v_add_f32_e32 v253, v149, v251
	v_add_f32_e32 v252, v253, v252
	v_add_f32_e32 v131, v131, v252
	v_cvt_pk_bf16_f32 v108, v236, v237
	v_cvt_pk_bf16_f32 v109, v238, v239
	v_cvt_pk_bf16_f32 v110, v240, v241
	v_cvt_pk_bf16_f32 v111, v242, v243
	v_cvt_pk_bf16_f32 v104, v244, v245
	v_cvt_pk_bf16_f32 v105, v246, v247
	v_cvt_pk_bf16_f32 v106, v248, v249
	v_cvt_pk_bf16_f32 v107, v250, v251
	v_cvt_pk_bf16_f32 v100, v134, v135
	v_cvt_pk_bf16_f32 v101, v136, v137
	v_cvt_pk_bf16_f32 v102, v138, v139
	v_cvt_pk_bf16_f32 v103, v140, v141
	v_cvt_pk_bf16_f32 v96, v142, v143
	v_cvt_pk_bf16_f32 v97, v144, v145
	v_cvt_pk_bf16_f32 v98, v146, v147
	v_cvt_pk_bf16_f32 v99, v148, v149
	s_branch .Lmb1_B_tail
.Lmb1_B_noqk:
	s_lshr_b32 s44, s34, 2
	s_cmp_eq_u32 s44, s91
	s_cselect_b64 s[8:9], -1, 0
	s_lshl_b32 s44, 1, s44
	v_and_b32_e32 v96, s44, v129
	v_cmp_ne_u32_e32 vcc, 0, v96
	s_or_b64 vcc, s[8:9], vcc
	s_nop 0
	v_cndmask_b32_e32 v96, v127, v112, vcc
	v_lshl_add_u32 v96, v96, 2, 0
	v_add_u32_e32 v104, 0x1d000, v96
	ds_read2_b32 v[96:97], v104 offset0:58 offset1:59
	ds_read2_b32 v[98:99], v104 offset0:26 offset1:27
	ds_read2_b32 v[100:101], v104 offset0:56 offset1:57
	s_waitcnt lgkmcnt(2)
	v_pk_add_f32 v[236:237], v[236:237], v[96:97] op_sel:[0,1] op_sel_hi:[1,0]
	ds_read2_b32 v[96:97], v104 offset0:24 offset1:25
	s_waitcnt lgkmcnt(2)
	v_pk_add_f32 v[134:135], v[134:135], v[98:99] op_sel:[0,1] op_sel_hi:[1,0]
	ds_read2_b32 v[98:99], v104 offset0:50 offset1:51
	s_waitcnt lgkmcnt(2)
	v_pk_add_f32 v[238:239], v[238:239], v[100:101] op_sel:[0,1] op_sel_hi:[1,0]
	ds_read2_b32 v[100:101], v104 offset0:18 offset1:19
	s_waitcnt lgkmcnt(1)
	v_pk_add_f32 v[240:241], v[240:241], v[98:99] op_sel:[0,1] op_sel_hi:[1,0]
	ds_read2_b32 v[98:99], v104 offset0:16 offset1:17
	s_waitcnt lgkmcnt(1)
	v_pk_add_f32 v[138:139], v[138:139], v[100:101] op_sel:[0,1] op_sel_hi:[1,0]
	ds_read2_b32 v[100:101], v104 offset0:42 offset1:43
	v_pk_add_f32 v[136:137], v[136:137], v[96:97] op_sel:[0,1] op_sel_hi:[1,0]
	ds_read2_b32 v[96:97], v104 offset0:48 offset1:49
	s_waitcnt lgkmcnt(1)
	v_pk_add_f32 v[244:245], v[244:245], v[100:101] op_sel:[0,1] op_sel_hi:[1,0]
	ds_read2_b32 v[100:101], v104 offset0:8 offset1:9
	s_waitcnt lgkmcnt(1)
	v_pk_add_f32 v[242:243], v[242:243], v[96:97] op_sel:[0,1] op_sel_hi:[1,0]
	ds_read2_b32 v[96:97], v104 offset0:10 offset1:11
	v_pk_add_f32 v[140:141], v[140:141], v[98:99] op_sel:[0,1] op_sel_hi:[1,0]
	ds_read2_b32 v[98:99], v104 offset0:40 offset1:41
	s_waitcnt lgkmcnt(2)
	v_pk_add_f32 v[144:145], v[144:145], v[100:101] op_sel:[0,1] op_sel_hi:[1,0]
	s_waitcnt lgkmcnt(1)
	v_pk_add_f32 v[142:143], v[142:143], v[96:97] op_sel:[0,1] op_sel_hi:[1,0]
	ds_read2_b32 v[96:97], v104 offset0:34 offset1:35
	s_waitcnt lgkmcnt(1)
	v_pk_add_f32 v[246:247], v[246:247], v[98:99] op_sel:[0,1] op_sel_hi:[1,0]
	ds_read2_b32 v[98:99], v104 offset0:2 offset1:3
	ds_read2_b32 v[102:103], v104 offset0:32 offset1:33
	ds_read2_b32 v[104:105], v104 offset1:1
	s_waitcnt lgkmcnt(3)
	v_pk_add_f32 v[248:249], v[248:249], v[96:97] op_sel:[0,1] op_sel_hi:[1,0]
	s_waitcnt lgkmcnt(2)
	v_pk_add_f32 v[146:147], v[146:147], v[98:99] op_sel:[0,1] op_sel_hi:[1,0]
	s_waitcnt lgkmcnt(1)
	v_pk_add_f32 v[250:251], v[250:251], v[102:103] op_sel:[0,1] op_sel_hi:[1,0]
	s_waitcnt lgkmcnt(0)
	v_pk_add_f32 v[148:149], v[148:149], v[104:105] op_sel:[0,1] op_sel_hi:[1,0]
	s_waitcnt lgkmcnt(0)
	ds_read_b64_tr_b16 v[186:187], v218
	ds_read_b64_tr_b16 v[188:189], v218 offset:512
	ds_read_b64_tr_b16 v[190:191], v218 offset:1024
	ds_read_b64_tr_b16 v[192:193], v218 offset:1536
	ds_read_b64_tr_b16 v[194:195], v218 offset:2048
	ds_read_b64_tr_b16 v[196:197], v218 offset:2560
	ds_read_b64_tr_b16 v[198:199], v218 offset:3072
	ds_read_b64_tr_b16 v[200:201], v218 offset:3584
	ds_read_b64_tr_b16 v[202:203], v218 offset:4096
	ds_read_b64_tr_b16 v[204:205], v218 offset:4608
	ds_read_b64_tr_b16 v[206:207], v218 offset:5120
	ds_read_b64_tr_b16 v[208:209], v218 offset:5632
	ds_read_b64_tr_b16 v[210:211], v218 offset:6144
	ds_read_b64_tr_b16 v[212:213], v218 offset:6656
	ds_read_b64_tr_b16 v[214:215], v218 offset:7168
	ds_read_b64_tr_b16 v[216:217], v218 offset:7680
	v_exp_f32_e32 v236, v236
	v_exp_f32_e32 v134, v134
	v_exp_f32_e32 v237, v237
	v_exp_f32_e32 v135, v135
	v_exp_f32_e32 v238, v238
	v_exp_f32_e32 v136, v136
	v_exp_f32_e32 v239, v239
	v_exp_f32_e32 v137, v137
	v_add_f32_e32 v252, v134, v236
	v_exp_f32_e32 v240, v240
	v_exp_f32_e32 v138, v138
	v_add_f32_e32 v252, 0, v252
	v_add_f32_e32 v253, v135, v237
	v_exp_f32_e32 v241, v241
	v_exp_f32_e32 v139, v139
	v_add_f32_e32 v252, v253, v252
	v_add_f32_e32 v253, v136, v238
	v_exp_f32_e32 v242, v242
	v_exp_f32_e32 v140, v140
	v_add_f32_e32 v252, v253, v252
	v_add_f32_e32 v253, v137, v239
	v_exp_f32_e32 v243, v243
	v_exp_f32_e32 v141, v141
	v_add_f32_e32 v252, v253, v252
	v_add_f32_e32 v253, v138, v240
	v_exp_f32_e32 v244, v244
	v_exp_f32_e32 v142, v142
	v_add_f32_e32 v252, v253, v252
	v_add_f32_e32 v253, v139, v241
	v_exp_f32_e32 v245, v245
	v_exp_f32_e32 v143, v143
	v_add_f32_e32 v252, v253, v252
	v_add_f32_e32 v253, v140, v242
	v_exp_f32_e32 v246, v246
	v_exp_f32_e32 v144, v144
	v_add_f32_e32 v252, v253, v252
	v_add_f32_e32 v253, v141, v243
	v_exp_f32_e32 v247, v247
	v_exp_f32_e32 v145, v145
	v_add_f32_e32 v252, v253, v252
	v_add_f32_e32 v253, v142, v244
	v_exp_f32_e32 v248, v248
	v_exp_f32_e32 v146, v146
	v_add_f32_e32 v252, v253, v252
	v_add_f32_e32 v253, v143, v245
	v_exp_f32_e32 v249, v249
	v_exp_f32_e32 v147, v147
	v_add_f32_e32 v252, v253, v252
	v_add_f32_e32 v253, v144, v246
	v_exp_f32_e32 v250, v250
	v_exp_f32_e32 v148, v148
	v_add_f32_e32 v252, v253, v252
	v_add_f32_e32 v253, v145, v247
	v_exp_f32_e32 v251, v251
	v_exp_f32_e32 v149, v149
	v_add_f32_e32 v252, v253, v252
	v_add_f32_e32 v253, v146, v248
	v_add_f32_e32 v252, v253, v252
	v_add_f32_e32 v253, v147, v249
	v_add_f32_e32 v252, v253, v252
	v_add_f32_e32 v253, v148, v250
	v_add_f32_e32 v252, v253, v252
	v_add_f32_e32 v253, v149, v251
	v_add_f32_e32 v252, v253, v252
	v_add_f32_e32 v131, v131, v252
	v_cvt_pk_bf16_f32 v108, v236, v237
	v_cvt_pk_bf16_f32 v109, v238, v239
	v_cvt_pk_bf16_f32 v110, v240, v241
	v_cvt_pk_bf16_f32 v111, v242, v243
	v_cvt_pk_bf16_f32 v104, v244, v245
	v_cvt_pk_bf16_f32 v105, v246, v247
	v_cvt_pk_bf16_f32 v106, v248, v249
	v_cvt_pk_bf16_f32 v107, v250, v251
	v_cvt_pk_bf16_f32 v100, v134, v135
	v_cvt_pk_bf16_f32 v101, v136, v137
	v_cvt_pk_bf16_f32 v102, v138, v139
	v_cvt_pk_bf16_f32 v103, v140, v141
	v_cvt_pk_bf16_f32 v96, v142, v143
	v_cvt_pk_bf16_f32 v97, v144, v145
	v_cvt_pk_bf16_f32 v98, v146, v147
	v_cvt_pk_bf16_f32 v99, v148, v149
	s_branch .Lmb1_B_tail

.Lmb3_skVAn:
.Lmb3_A_g0near:
	s_lshr_b32 s42, s3, 1
	s_add_i32 s42, s42, s29
	s_add_i32 s42, s42, 3
	s_sub_i32 s42, s30, s42
	s_cmp_gt_i32 s42, 0
	s_cbranch_scc1 .Lmb3_A_tail
	s_waitcnt lgkmcnt(8)
	v_mfma_f32_32x32x16_bf16 v[16:31], v[108:111], v[186:189], v[16:31]
	v_mfma_f32_32x32x16_bf16 v[16:31], v[104:107], v[190:193], v[16:31]
	v_mfma_f32_32x32x16_bf16 v[16:31], v[100:103], v[194:197], v[16:31]
	v_mfma_f32_32x32x16_bf16 v[16:31], v[96:99], v[198:201], v[16:31]
	v_mfma_f32_32x32x16_bf16 v[32:47], v[108:111], v[202:205], v[32:47]
	v_mfma_f32_32x32x16_bf16 v[32:47], v[104:107], v[206:209], v[32:47]
	v_mfma_f32_32x32x16_bf16 v[32:47], v[100:103], v[210:213], v[32:47]
	v_mfma_f32_32x32x16_bf16 v[32:47], v[96:99], v[214:217], v[32:47]
	s_cmp_eq_u32 s42, 0
	s_cbranch_scc1 .Lmb3_A_zpw
	s_cmp_eq_i32 s42, -1
	s_cbranch_scc1 .Lmb3_A_noqk
	s_lshr_b32 s42, s30, 2
	s_cmp_eq_u32 s42, s93
	s_cselect_b64 s[10:11], -1, 0
	s_lshl_b32 s42, 1, s42
	v_and_b32_e32 v96, s42, v129
	v_cmp_ne_u32_e32 vcc, 0, v96
	s_or_b64 vcc, s[10:11], vcc
	s_nop 0
	v_cndmask_b32_e32 v96, v127, v112, vcc
	v_lshl_add_u32 v96, v96, 2, 0
	v_add_u32_e32 v104, 0x1d000, v96
	ds_read2_b32 v[96:97], v104 offset0:58 offset1:59
	ds_read2_b32 v[98:99], v104 offset0:26 offset1:27
	ds_read2_b32 v[100:101], v104 offset0:56 offset1:57
	s_waitcnt lgkmcnt(2)
	v_pk_add_f32 v[64:65], v[64:65], v[96:97] op_sel:[0,1] op_sel_hi:[1,0]
	ds_read2_b32 v[96:97], v104 offset0:24 offset1:25
	s_waitcnt lgkmcnt(2)
	v_pk_add_f32 v[48:49], v[48:49], v[98:99] op_sel:[0,1] op_sel_hi:[1,0]
	ds_read2_b32 v[98:99], v104 offset0:50 offset1:51
	s_waitcnt lgkmcnt(2)
	v_pk_add_f32 v[66:67], v[66:67], v[100:101] op_sel:[0,1] op_sel_hi:[1,0]
	ds_read2_b32 v[100:101], v104 offset0:18 offset1:19
	s_waitcnt lgkmcnt(1)
	v_pk_add_f32 v[68:69], v[68:69], v[98:99] op_sel:[0,1] op_sel_hi:[1,0]
	ds_read2_b32 v[98:99], v104 offset0:16 offset1:17
	s_waitcnt lgkmcnt(1)
	v_pk_add_f32 v[52:53], v[52:53], v[100:101] op_sel:[0,1] op_sel_hi:[1,0]
	ds_read2_b32 v[100:101], v104 offset0:42 offset1:43
	v_pk_add_f32 v[50:51], v[50:51], v[96:97] op_sel:[0,1] op_sel_hi:[1,0]
	ds_read2_b32 v[96:97], v104 offset0:48 offset1:49
	s_waitcnt lgkmcnt(1)
	v_pk_add_f32 v[72:73], v[72:73], v[100:101] op_sel:[0,1] op_sel_hi:[1,0]
	ds_read2_b32 v[100:101], v104 offset0:8 offset1:9
	s_waitcnt lgkmcnt(1)
	v_pk_add_f32 v[70:71], v[70:71], v[96:97] op_sel:[0,1] op_sel_hi:[1,0]
	ds_read2_b32 v[96:97], v104 offset0:10 offset1:11
	v_pk_add_f32 v[54:55], v[54:55], v[98:99] op_sel:[0,1] op_sel_hi:[1,0]
	ds_read2_b32 v[98:99], v104 offset0:40 offset1:41
	s_waitcnt lgkmcnt(2)
	v_pk_add_f32 v[58:59], v[58:59], v[100:101] op_sel:[0,1] op_sel_hi:[1,0]
	s_waitcnt lgkmcnt(1)
	v_pk_add_f32 v[56:57], v[56:57], v[96:97] op_sel:[0,1] op_sel_hi:[1,0]
	ds_read2_b32 v[96:97], v104 offset0:34 offset1:35
	s_waitcnt lgkmcnt(1)
	v_pk_add_f32 v[74:75], v[74:75], v[98:99] op_sel:[0,1] op_sel_hi:[1,0]
	ds_read2_b32 v[98:99], v104 offset0:2 offset1:3
	ds_read2_b32 v[102:103], v104 offset0:32 offset1:33
	ds_read2_b32 v[104:105], v104 offset1:1
	s_waitcnt lgkmcnt(3)
	v_pk_add_f32 v[76:77], v[76:77], v[96:97] op_sel:[0,1] op_sel_hi:[1,0]
	s_waitcnt lgkmcnt(2)
	v_pk_add_f32 v[60:61], v[60:61], v[98:99] op_sel:[0,1] op_sel_hi:[1,0]
	s_waitcnt lgkmcnt(1)
	v_pk_add_f32 v[78:79], v[78:79], v[102:103] op_sel:[0,1] op_sel_hi:[1,0]
	s_waitcnt lgkmcnt(0)
	v_pk_add_f32 v[62:63], v[62:63], v[104:105] op_sel:[0,1] op_sel_hi:[1,0]
	s_waitcnt lgkmcnt(0)
	v_mfma_f32_32x32x16_bf16 v[236:251], v[154:157], v[92:95], v[220:235]
	ds_read_b64_tr_b16 v[186:187], v218
	ds_read_b64_tr_b16 v[188:189], v218 offset:512
	ds_read_b64_tr_b16 v[190:191], v218 offset:1024
	ds_read_b64_tr_b16 v[192:193], v218 offset:1536
	ds_read_b64_tr_b16 v[194:195], v218 offset:2048
	ds_read_b64_tr_b16 v[196:197], v218 offset:2560
	ds_read_b64_tr_b16 v[198:199], v218 offset:3072
	ds_read_b64_tr_b16 v[200:201], v218 offset:3584
	ds_read_b64_tr_b16 v[202:203], v218 offset:4096
	ds_read_b64_tr_b16 v[204:205], v218 offset:4608
	ds_read_b64_tr_b16 v[206:207], v218 offset:5120
	v_mfma_f32_32x32x16_bf16 v[134:149], v[158:161], v[92:95], v[220:235]
	ds_read_b64_tr_b16 v[208:209], v218 offset:5632
	ds_read_b64_tr_b16 v[210:211], v218 offset:6144
	ds_read_b64_tr_b16 v[212:213], v218 offset:6656
	ds_read_b64_tr_b16 v[214:215], v218 offset:7168
	ds_read_b64_tr_b16 v[216:217], v218 offset:7680
	v_exp_f32_e32 v64, v64
	v_exp_f32_e32 v48, v48
	v_exp_f32_e32 v65, v65
	v_exp_f32_e32 v49, v49
	v_exp_f32_e32 v66, v66
	v_exp_f32_e32 v50, v50
	v_mfma_f32_32x32x16_bf16 v[236:251], v[162:165], v[88:91], v[236:251]
	v_exp_f32_e32 v67, v67
	v_exp_f32_e32 v51, v51
	v_add_f32_e32 v252, v48, v64
	v_exp_f32_e32 v68, v68
	v_exp_f32_e32 v52, v52
	v_add_f32_e32 v252, 0, v252
	v_add_f32_e32 v253, v49, v65
	v_exp_f32_e32 v69, v69
	v_exp_f32_e32 v53, v53
	v_add_f32_e32 v252, v253, v252
	v_add_f32_e32 v253, v50, v66
	v_mfma_f32_32x32x16_bf16 v[134:149], v[166:169], v[88:91], v[134:149]
	v_exp_f32_e32 v70, v70
	v_exp_f32_e32 v54, v54
	v_add_f32_e32 v252, v253, v252
	v_add_f32_e32 v253, v51, v67
	v_exp_f32_e32 v71, v71
	v_exp_f32_e32 v55, v55
	v_add_f32_e32 v252, v253, v252
	v_add_f32_e32 v253, v52, v68
	v_exp_f32_e32 v72, v72
	v_exp_f32_e32 v56, v56
	v_add_f32_e32 v252, v253, v252
	v_mfma_f32_32x32x16_bf16 v[236:251], v[170:173], v[84:87], v[236:251]
	v_add_f32_e32 v253, v53, v69
	v_exp_f32_e32 v73, v73
	v_exp_f32_e32 v57, v57
	v_add_f32_e32 v252, v253, v252
	v_add_f32_e32 v253, v54, v70
	v_exp_f32_e32 v74, v74
	v_exp_f32_e32 v58, v58
	v_add_f32_e32 v252, v253, v252
	v_add_f32_e32 v253, v55, v71
	v_exp_f32_e32 v75, v75
	v_exp_f32_e32 v59, v59
	v_mfma_f32_32x32x16_bf16 v[134:149], v[174:177], v[84:87], v[134:149]
	v_add_f32_e32 v252, v253, v252
	v_add_f32_e32 v253, v56, v72
	v_exp_f32_e32 v76, v76
	v_exp_f32_e32 v60, v60
	v_add_f32_e32 v252, v253, v252
	v_add_f32_e32 v253, v57, v73
	v_exp_f32_e32 v77, v77
	v_exp_f32_e32 v61, v61
	v_add_f32_e32 v252, v253, v252
	v_add_f32_e32 v253, v58, v74
	v_exp_f32_e32 v78, v78
	v_mfma_f32_32x32x16_bf16 v[236:251], v[178:181], v[80:83], v[236:251]
	v_exp_f32_e32 v62, v62
	v_add_f32_e32 v252, v253, v252
	v_add_f32_e32 v253, v59, v75
	v_exp_f32_e32 v79, v79
	v_exp_f32_e32 v63, v63
	v_add_f32_e32 v252, v253, v252
	v_add_f32_e32 v253, v60, v76
	v_add_f32_e32 v252, v253, v252
	v_add_f32_e32 v253, v61, v77
	v_add_f32_e32 v252, v253, v252
	v_add_f32_e32 v253, v62, v78
	v_mfma_f32_32x32x16_bf16 v[134:149], v[182:185], v[80:83], v[134:149]
	v_add_f32_e32 v252, v253, v252
	v_add_f32_e32 v253, v63, v79
	v_add_f32_e32 v252, v253, v252
	v_add_f32_e32 v131, v131, v252
	v_cvt_pk_bf16_f32 v108, v64, v65
	v_cvt_pk_bf16_f32 v109, v66, v67
	v_cvt_pk_bf16_f32 v110, v68, v69
	v_cvt_pk_bf16_f32 v111, v70, v71
	v_cvt_pk_bf16_f32 v104, v72, v73
	v_cvt_pk_bf16_f32 v105, v74, v75
	v_cvt_pk_bf16_f32 v106, v76, v77
	v_cvt_pk_bf16_f32 v107, v78, v79
	v_cvt_pk_bf16_f32 v100, v48, v49
	v_cvt_pk_bf16_f32 v101, v50, v51
	v_cvt_pk_bf16_f32 v102, v52, v53
	v_cvt_pk_bf16_f32 v103, v54, v55
	v_cvt_pk_bf16_f32 v96, v56, v57
	v_cvt_pk_bf16_f32 v97, v58, v59
	v_cvt_pk_bf16_f32 v98, v60, v61
	v_cvt_pk_bf16_f32 v99, v62, v63
	s_branch .Lmb3_A_tail
.Lmb3_A_noqk:
	s_lshr_b32 s42, s30, 2
	s_cmp_eq_u32 s42, s93
	s_cselect_b64 s[10:11], -1, 0
	s_lshl_b32 s42, 1, s42
	v_and_b32_e32 v96, s42, v129
	v_cmp_ne_u32_e32 vcc, 0, v96
	s_or_b64 vcc, s[10:11], vcc
	s_nop 0
	v_cndmask_b32_e32 v96, v127, v112, vcc
	v_lshl_add_u32 v96, v96, 2, 0
	v_add_u32_e32 v104, 0x1d000, v96
	ds_read2_b32 v[96:97], v104 offset0:58 offset1:59
	ds_read2_b32 v[98:99], v104 offset0:26 offset1:27
	ds_read2_b32 v[100:101], v104 offset0:56 offset1:57
	s_waitcnt lgkmcnt(2)
	v_pk_add_f32 v[64:65], v[64:65], v[96:97] op_sel:[0,1] op_sel_hi:[1,0]
	ds_read2_b32 v[96:97], v104 offset0:24 offset1:25
	s_waitcnt lgkmcnt(2)
	v_pk_add_f32 v[48:49], v[48:49], v[98:99] op_sel:[0,1] op_sel_hi:[1,0]
	ds_read2_b32 v[98:99], v104 offset0:50 offset1:51
	s_waitcnt lgkmcnt(2)
	v_pk_add_f32 v[66:67], v[66:67], v[100:101] op_sel:[0,1] op_sel_hi:[1,0]
	ds_read2_b32 v[100:101], v104 offset0:18 offset1:19
	s_waitcnt lgkmcnt(1)
	v_pk_add_f32 v[68:69], v[68:69], v[98:99] op_sel:[0,1] op_sel_hi:[1,0]
	ds_read2_b32 v[98:99], v104 offset0:16 offset1:17
	s_waitcnt lgkmcnt(1)
	v_pk_add_f32 v[52:53], v[52:53], v[100:101] op_sel:[0,1] op_sel_hi:[1,0]
	ds_read2_b32 v[100:101], v104 offset0:42 offset1:43
	v_pk_add_f32 v[50:51], v[50:51], v[96:97] op_sel:[0,1] op_sel_hi:[1,0]
	ds_read2_b32 v[96:97], v104 offset0:48 offset1:49
	s_waitcnt lgkmcnt(1)
	v_pk_add_f32 v[72:73], v[72:73], v[100:101] op_sel:[0,1] op_sel_hi:[1,0]
	ds_read2_b32 v[100:101], v104 offset0:8 offset1:9
	s_waitcnt lgkmcnt(1)
	v_pk_add_f32 v[70:71], v[70:71], v[96:97] op_sel:[0,1] op_sel_hi:[1,0]
	ds_read2_b32 v[96:97], v104 offset0:10 offset1:11
	v_pk_add_f32 v[54:55], v[54:55], v[98:99] op_sel:[0,1] op_sel_hi:[1,0]
	ds_read2_b32 v[98:99], v104 offset0:40 offset1:41
	s_waitcnt lgkmcnt(2)
	v_pk_add_f32 v[58:59], v[58:59], v[100:101] op_sel:[0,1] op_sel_hi:[1,0]
	s_waitcnt lgkmcnt(1)
	v_pk_add_f32 v[56:57], v[56:57], v[96:97] op_sel:[0,1] op_sel_hi:[1,0]
	ds_read2_b32 v[96:97], v104 offset0:34 offset1:35
	s_waitcnt lgkmcnt(1)
	v_pk_add_f32 v[74:75], v[74:75], v[98:99] op_sel:[0,1] op_sel_hi:[1,0]
	ds_read2_b32 v[98:99], v104 offset0:2 offset1:3
	ds_read2_b32 v[102:103], v104 offset0:32 offset1:33
	ds_read2_b32 v[104:105], v104 offset1:1
	s_waitcnt lgkmcnt(3)
	v_pk_add_f32 v[76:77], v[76:77], v[96:97] op_sel:[0,1] op_sel_hi:[1,0]
	s_waitcnt lgkmcnt(2)
	v_pk_add_f32 v[60:61], v[60:61], v[98:99] op_sel:[0,1] op_sel_hi:[1,0]
	s_waitcnt lgkmcnt(1)
	v_pk_add_f32 v[78:79], v[78:79], v[102:103] op_sel:[0,1] op_sel_hi:[1,0]
	s_waitcnt lgkmcnt(0)
	v_pk_add_f32 v[62:63], v[62:63], v[104:105] op_sel:[0,1] op_sel_hi:[1,0]
	s_waitcnt lgkmcnt(0)
	ds_read_b64_tr_b16 v[186:187], v218
	ds_read_b64_tr_b16 v[188:189], v218 offset:512
	ds_read_b64_tr_b16 v[190:191], v218 offset:1024
	ds_read_b64_tr_b16 v[192:193], v218 offset:1536
	ds_read_b64_tr_b16 v[194:195], v218 offset:2048
	ds_read_b64_tr_b16 v[196:197], v218 offset:2560
	ds_read_b64_tr_b16 v[198:199], v218 offset:3072
	ds_read_b64_tr_b16 v[200:201], v218 offset:3584
	ds_read_b64_tr_b16 v[202:203], v218 offset:4096
	ds_read_b64_tr_b16 v[204:205], v218 offset:4608
	ds_read_b64_tr_b16 v[206:207], v218 offset:5120
	ds_read_b64_tr_b16 v[208:209], v218 offset:5632
	ds_read_b64_tr_b16 v[210:211], v218 offset:6144
	ds_read_b64_tr_b16 v[212:213], v218 offset:6656
	ds_read_b64_tr_b16 v[214:215], v218 offset:7168
	ds_read_b64_tr_b16 v[216:217], v218 offset:7680
	v_exp_f32_e32 v64, v64
	v_exp_f32_e32 v48, v48
	v_exp_f32_e32 v65, v65
	v_exp_f32_e32 v49, v49
	v_exp_f32_e32 v66, v66
	v_exp_f32_e32 v50, v50
	v_exp_f32_e32 v67, v67
	v_exp_f32_e32 v51, v51
	v_add_f32_e32 v252, v48, v64
	v_exp_f32_e32 v68, v68
	v_exp_f32_e32 v52, v52
	v_add_f32_e32 v252, 0, v252
	v_add_f32_e32 v253, v49, v65
	v_exp_f32_e32 v69, v69
	v_exp_f32_e32 v53, v53
	v_add_f32_e32 v252, v253, v252
	v_add_f32_e32 v253, v50, v66
	v_exp_f32_e32 v70, v70
	v_exp_f32_e32 v54, v54
	v_add_f32_e32 v252, v253, v252
	v_add_f32_e32 v253, v51, v67
	v_exp_f32_e32 v71, v71
	v_exp_f32_e32 v55, v55
	v_add_f32_e32 v252, v253, v252
	v_add_f32_e32 v253, v52, v68
	v_exp_f32_e32 v72, v72
	v_exp_f32_e32 v56, v56
	v_add_f32_e32 v252, v253, v252
	v_add_f32_e32 v253, v53, v69
	v_exp_f32_e32 v73, v73
	v_exp_f32_e32 v57, v57
	v_add_f32_e32 v252, v253, v252
	v_add_f32_e32 v253, v54, v70
	v_exp_f32_e32 v74, v74
	v_exp_f32_e32 v58, v58
	v_add_f32_e32 v252, v253, v252
	v_add_f32_e32 v253, v55, v71
	v_exp_f32_e32 v75, v75
	v_exp_f32_e32 v59, v59
	v_add_f32_e32 v252, v253, v252
	v_add_f32_e32 v253, v56, v72
	v_exp_f32_e32 v76, v76
	v_exp_f32_e32 v60, v60
	v_add_f32_e32 v252, v253, v252
	v_add_f32_e32 v253, v57, v73
	v_exp_f32_e32 v77, v77
	v_exp_f32_e32 v61, v61
	v_add_f32_e32 v252, v253, v252
	v_add_f32_e32 v253, v58, v74
	v_exp_f32_e32 v78, v78
	v_exp_f32_e32 v62, v62
	v_add_f32_e32 v252, v253, v252
	v_add_f32_e32 v253, v59, v75
	v_exp_f32_e32 v79, v79
	v_exp_f32_e32 v63, v63
	v_add_f32_e32 v252, v253, v252
	v_add_f32_e32 v253, v60, v76
	v_add_f32_e32 v252, v253, v252
	v_add_f32_e32 v253, v61, v77
	v_add_f32_e32 v252, v253, v252
	v_add_f32_e32 v253, v62, v78
	v_add_f32_e32 v252, v253, v252
	v_add_f32_e32 v253, v63, v79
	v_add_f32_e32 v252, v253, v252
	v_add_f32_e32 v131, v131, v252
	v_cvt_pk_bf16_f32 v108, v64, v65
	v_cvt_pk_bf16_f32 v109, v66, v67
	v_cvt_pk_bf16_f32 v110, v68, v69
	v_cvt_pk_bf16_f32 v111, v70, v71
	v_cvt_pk_bf16_f32 v104, v72, v73
	v_cvt_pk_bf16_f32 v105, v74, v75
	v_cvt_pk_bf16_f32 v106, v76, v77
	v_cvt_pk_bf16_f32 v107, v78, v79
	v_cvt_pk_bf16_f32 v100, v48, v49
	v_cvt_pk_bf16_f32 v101, v50, v51
	v_cvt_pk_bf16_f32 v102, v52, v53
	v_cvt_pk_bf16_f32 v103, v54, v55
	v_cvt_pk_bf16_f32 v96, v56, v57
	v_cvt_pk_bf16_f32 v97, v58, v59
	v_cvt_pk_bf16_f32 v98, v60, v61
	v_cvt_pk_bf16_f32 v99, v62, v63
	s_branch .Lmb3_A_tail

.Lmb3_skVBn:
.Lmb3_B_g0near:
	s_lshr_b32 s42, s3, 1
	s_add_i32 s42, s42, s29
	s_add_i32 s42, s42, 3
	s_sub_i32 s42, s30, s42
	s_cmp_gt_i32 s42, 0
	s_cbranch_scc1 .Lmb3_B_tail
	s_waitcnt lgkmcnt(8)
	v_mfma_f32_32x32x16_bf16 v[16:31], v[108:111], v[186:189], v[16:31]
	v_mfma_f32_32x32x16_bf16 v[16:31], v[104:107], v[190:193], v[16:31]
	v_mfma_f32_32x32x16_bf16 v[16:31], v[100:103], v[194:197], v[16:31]
	v_mfma_f32_32x32x16_bf16 v[16:31], v[96:99], v[198:201], v[16:31]
	v_mfma_f32_32x32x16_bf16 v[32:47], v[108:111], v[202:205], v[32:47]
	v_mfma_f32_32x32x16_bf16 v[32:47], v[104:107], v[206:209], v[32:47]
	v_mfma_f32_32x32x16_bf16 v[32:47], v[100:103], v[210:213], v[32:47]
	v_mfma_f32_32x32x16_bf16 v[32:47], v[96:99], v[214:217], v[32:47]
	s_cmp_eq_u32 s42, 0
	s_cbranch_scc1 .Lmb3_B_zpw
	s_cmp_eq_i32 s42, -1
	s_cbranch_scc1 .Lmb3_B_noqk
	s_lshr_b32 s42, s30, 2
	s_cmp_eq_u32 s42, s93
	s_cselect_b64 s[10:11], -1, 0
	s_lshl_b32 s42, 1, s42
	v_and_b32_e32 v96, s42, v129
	v_cmp_ne_u32_e32 vcc, 0, v96
	s_or_b64 vcc, s[10:11], vcc
	s_nop 0
	v_cndmask_b32_e32 v96, v127, v112, vcc
	v_lshl_add_u32 v96, v96, 2, 0
	v_add_u32_e32 v104, 0x1d000, v96
	ds_read2_b32 v[96:97], v104 offset0:58 offset1:59
	ds_read2_b32 v[98:99], v104 offset0:26 offset1:27
	ds_read2_b32 v[100:101], v104 offset0:56 offset1:57
	s_waitcnt lgkmcnt(2)
	v_pk_add_f32 v[236:237], v[236:237], v[96:97] op_sel:[0,1] op_sel_hi:[1,0]
	ds_read2_b32 v[96:97], v104 offset0:24 offset1:25
	s_waitcnt lgkmcnt(2)
	v_pk_add_f32 v[134:135], v[134:135], v[98:99] op_sel:[0,1] op_sel_hi:[1,0]
	ds_read2_b32 v[98:99], v104 offset0:50 offset1:51
	s_waitcnt lgkmcnt(2)
	v_pk_add_f32 v[238:239], v[238:239], v[100:101] op_sel:[0,1] op_sel_hi:[1,0]
	ds_read2_b32 v[100:101], v104 offset0:18 offset1:19
	s_waitcnt lgkmcnt(1)
	v_pk_add_f32 v[240:241], v[240:241], v[98:99] op_sel:[0,1] op_sel_hi:[1,0]
	ds_read2_b32 v[98:99], v104 offset0:16 offset1:17
	s_waitcnt lgkmcnt(1)
	v_pk_add_f32 v[138:139], v[138:139], v[100:101] op_sel:[0,1] op_sel_hi:[1,0]
	ds_read2_b32 v[100:101], v104 offset0:42 offset1:43
	v_pk_add_f32 v[136:137], v[136:137], v[96:97] op_sel:[0,1] op_sel_hi:[1,0]
	ds_read2_b32 v[96:97], v104 offset0:48 offset1:49
	s_waitcnt lgkmcnt(1)
	v_pk_add_f32 v[244:245], v[244:245], v[100:101] op_sel:[0,1] op_sel_hi:[1,0]
	ds_read2_b32 v[100:101], v104 offset0:8 offset1:9
	s_waitcnt lgkmcnt(1)
	v_pk_add_f32 v[242:243], v[242:243], v[96:97] op_sel:[0,1] op_sel_hi:[1,0]
	ds_read2_b32 v[96:97], v104 offset0:10 offset1:11
	v_pk_add_f32 v[140:141], v[140:141], v[98:99] op_sel:[0,1] op_sel_hi:[1,0]
	ds_read2_b32 v[98:99], v104 offset0:40 offset1:41
	s_waitcnt lgkmcnt(2)
	v_pk_add_f32 v[144:145], v[144:145], v[100:101] op_sel:[0,1] op_sel_hi:[1,0]
	s_waitcnt lgkmcnt(1)
	v_pk_add_f32 v[142:143], v[142:143], v[96:97] op_sel:[0,1] op_sel_hi:[1,0]
	ds_read2_b32 v[96:97], v104 offset0:34 offset1:35
	s_waitcnt lgkmcnt(1)
	v_pk_add_f32 v[246:247], v[246:247], v[98:99] op_sel:[0,1] op_sel_hi:[1,0]
	ds_read2_b32 v[98:99], v104 offset0:2 offset1:3
	ds_read2_b32 v[102:103], v104 offset0:32 offset1:33
	ds_read2_b32 v[104:105], v104 offset1:1
	s_waitcnt lgkmcnt(3)
	v_pk_add_f32 v[248:249], v[248:249], v[96:97] op_sel:[0,1] op_sel_hi:[1,0]
	s_waitcnt lgkmcnt(2)
	v_pk_add_f32 v[146:147], v[146:147], v[98:99] op_sel:[0,1] op_sel_hi:[1,0]
	s_waitcnt lgkmcnt(1)
	v_pk_add_f32 v[250:251], v[250:251], v[102:103] op_sel:[0,1] op_sel_hi:[1,0]
	s_waitcnt lgkmcnt(0)
	v_pk_add_f32 v[148:149], v[148:149], v[104:105] op_sel:[0,1] op_sel_hi:[1,0]
	s_waitcnt lgkmcnt(0)
	v_mfma_f32_32x32x16_bf16 v[64:79], v[154:157], v[92:95], v[220:235]
	ds_read_b64_tr_b16 v[186:187], v218
	ds_read_b64_tr_b16 v[188:189], v218 offset:512
	ds_read_b64_tr_b16 v[190:191], v218 offset:1024
	ds_read_b64_tr_b16 v[192:193], v218 offset:1536
	ds_read_b64_tr_b16 v[194:195], v218 offset:2048
	ds_read_b64_tr_b16 v[196:197], v218 offset:2560
	ds_read_b64_tr_b16 v[198:199], v218 offset:3072
	ds_read_b64_tr_b16 v[200:201], v218 offset:3584
	ds_read_b64_tr_b16 v[202:203], v218 offset:4096
	ds_read_b64_tr_b16 v[204:205], v218 offset:4608
	ds_read_b64_tr_b16 v[206:207], v218 offset:5120
	v_mfma_f32_32x32x16_bf16 v[48:63], v[158:161], v[92:95], v[220:235]
	ds_read_b64_tr_b16 v[208:209], v218 offset:5632
	ds_read_b64_tr_b16 v[210:211], v218 offset:6144
	ds_read_b64_tr_b16 v[212:213], v218 offset:6656
	ds_read_b64_tr_b16 v[214:215], v218 offset:7168
	ds_read_b64_tr_b16 v[216:217], v218 offset:7680
	v_exp_f32_e32 v236, v236
	v_exp_f32_e32 v134, v134
	v_exp_f32_e32 v237, v237
	v_exp_f32_e32 v135, v135
	v_exp_f32_e32 v238, v238
	v_exp_f32_e32 v136, v136
	v_mfma_f32_32x32x16_bf16 v[64:79], v[162:165], v[88:91], v[64:79]
	v_exp_f32_e32 v239, v239
	v_exp_f32_e32 v137, v137
	v_add_f32_e32 v252, v134, v236
	v_exp_f32_e32 v240, v240
	v_exp_f32_e32 v138, v138
	v_add_f32_e32 v252, 0, v252
	v_add_f32_e32 v253, v135, v237
	v_exp_f32_e32 v241, v241
	v_exp_f32_e32 v139, v139
	v_add_f32_e32 v252, v253, v252
	v_add_f32_e32 v253, v136, v238
	v_mfma_f32_32x32x16_bf16 v[48:63], v[166:169], v[88:91], v[48:63]
	v_exp_f32_e32 v242, v242
	v_exp_f32_e32 v140, v140
	v_add_f32_e32 v252, v253, v252
	v_add_f32_e32 v253, v137, v239
	v_exp_f32_e32 v243, v243
	v_exp_f32_e32 v141, v141
	v_add_f32_e32 v252, v253, v252
	v_add_f32_e32 v253, v138, v240
	v_exp_f32_e32 v244, v244
	v_exp_f32_e32 v142, v142
	v_add_f32_e32 v252, v253, v252
	v_mfma_f32_32x32x16_bf16 v[64:79], v[170:173], v[84:87], v[64:79]
	v_add_f32_e32 v253, v139, v241
	v_exp_f32_e32 v245, v245
	v_exp_f32_e32 v143, v143
	v_add_f32_e32 v252, v253, v252
	v_add_f32_e32 v253, v140, v242
	v_exp_f32_e32 v246, v246
	v_exp_f32_e32 v144, v144
	v_add_f32_e32 v252, v253, v252
	v_add_f32_e32 v253, v141, v243
	v_exp_f32_e32 v247, v247
	v_exp_f32_e32 v145, v145
	v_mfma_f32_32x32x16_bf16 v[48:63], v[174:177], v[84:87], v[48:63]
	v_add_f32_e32 v252, v253, v252
	v_add_f32_e32 v253, v142, v244
	v_exp_f32_e32 v248, v248
	v_exp_f32_e32 v146, v146
	v_add_f32_e32 v252, v253, v252
	v_add_f32_e32 v253, v143, v245
	v_exp_f32_e32 v249, v249
	v_exp_f32_e32 v147, v147
	v_add_f32_e32 v252, v253, v252
	v_add_f32_e32 v253, v144, v246
	v_exp_f32_e32 v250, v250
	v_mfma_f32_32x32x16_bf16 v[64:79], v[178:181], v[80:83], v[64:79]
	v_exp_f32_e32 v148, v148
	v_add_f32_e32 v252, v253, v252
	v_add_f32_e32 v253, v145, v247
	v_exp_f32_e32 v251, v251
	v_exp_f32_e32 v149, v149
	v_add_f32_e32 v252, v253, v252
	v_add_f32_e32 v253, v146, v248
	v_add_f32_e32 v252, v253, v252
	v_add_f32_e32 v253, v147, v249
	v_add_f32_e32 v252, v253, v252
	v_add_f32_e32 v253, v148, v250
	v_mfma_f32_32x32x16_bf16 v[48:63], v[182:185], v[80:83], v[48:63]
	v_add_f32_e32 v252, v253, v252
	v_add_f32_e32 v253, v149, v251
	v_add_f32_e32 v252, v253, v252
	v_add_f32_e32 v131, v131, v252
	v_cvt_pk_bf16_f32 v108, v236, v237
	v_cvt_pk_bf16_f32 v109, v238, v239
	v_cvt_pk_bf16_f32 v110, v240, v241
	v_cvt_pk_bf16_f32 v111, v242, v243
	v_cvt_pk_bf16_f32 v104, v244, v245
	v_cvt_pk_bf16_f32 v105, v246, v247
	v_cvt_pk_bf16_f32 v106, v248, v249
	v_cvt_pk_bf16_f32 v107, v250, v251
	v_cvt_pk_bf16_f32 v100, v134, v135
	v_cvt_pk_bf16_f32 v101, v136, v137
	v_cvt_pk_bf16_f32 v102, v138, v139
	v_cvt_pk_bf16_f32 v103, v140, v141
	v_cvt_pk_bf16_f32 v96, v142, v143
	v_cvt_pk_bf16_f32 v97, v144, v145
	v_cvt_pk_bf16_f32 v98, v146, v147
	v_cvt_pk_bf16_f32 v99, v148, v149
	s_branch .Lmb3_B_tail
.Lmb3_B_noqk:
	s_lshr_b32 s42, s30, 2
	s_cmp_eq_u32 s42, s93
	s_cselect_b64 s[10:11], -1, 0
	s_lshl_b32 s42, 1, s42
	v_and_b32_e32 v96, s42, v129
	v_cmp_ne_u32_e32 vcc, 0, v96
	s_or_b64 vcc, s[10:11], vcc
	s_nop 0
	v_cndmask_b32_e32 v96, v127, v112, vcc
	v_lshl_add_u32 v96, v96, 2, 0
	v_add_u32_e32 v104, 0x1d000, v96
	ds_read2_b32 v[96:97], v104 offset0:58 offset1:59
	ds_read2_b32 v[98:99], v104 offset0:26 offset1:27
	ds_read2_b32 v[100:101], v104 offset0:56 offset1:57
	s_waitcnt lgkmcnt(2)
	v_pk_add_f32 v[236:237], v[236:237], v[96:97] op_sel:[0,1] op_sel_hi:[1,0]
	ds_read2_b32 v[96:97], v104 offset0:24 offset1:25
	s_waitcnt lgkmcnt(2)
	v_pk_add_f32 v[134:135], v[134:135], v[98:99] op_sel:[0,1] op_sel_hi:[1,0]
	ds_read2_b32 v[98:99], v104 offset0:50 offset1:51
	s_waitcnt lgkmcnt(2)
	v_pk_add_f32 v[238:239], v[238:239], v[100:101] op_sel:[0,1] op_sel_hi:[1,0]
	ds_read2_b32 v[100:101], v104 offset0:18 offset1:19
	s_waitcnt lgkmcnt(1)
	v_pk_add_f32 v[240:241], v[240:241], v[98:99] op_sel:[0,1] op_sel_hi:[1,0]
	ds_read2_b32 v[98:99], v104 offset0:16 offset1:17
	s_waitcnt lgkmcnt(1)
	v_pk_add_f32 v[138:139], v[138:139], v[100:101] op_sel:[0,1] op_sel_hi:[1,0]
	ds_read2_b32 v[100:101], v104 offset0:42 offset1:43
	v_pk_add_f32 v[136:137], v[136:137], v[96:97] op_sel:[0,1] op_sel_hi:[1,0]
	ds_read2_b32 v[96:97], v104 offset0:48 offset1:49
	s_waitcnt lgkmcnt(1)
	v_pk_add_f32 v[244:245], v[244:245], v[100:101] op_sel:[0,1] op_sel_hi:[1,0]
	ds_read2_b32 v[100:101], v104 offset0:8 offset1:9
	s_waitcnt lgkmcnt(1)
	v_pk_add_f32 v[242:243], v[242:243], v[96:97] op_sel:[0,1] op_sel_hi:[1,0]
	ds_read2_b32 v[96:97], v104 offset0:10 offset1:11
	v_pk_add_f32 v[140:141], v[140:141], v[98:99] op_sel:[0,1] op_sel_hi:[1,0]
	ds_read2_b32 v[98:99], v104 offset0:40 offset1:41
	s_waitcnt lgkmcnt(2)
	v_pk_add_f32 v[144:145], v[144:145], v[100:101] op_sel:[0,1] op_sel_hi:[1,0]
	s_waitcnt lgkmcnt(1)
	v_pk_add_f32 v[142:143], v[142:143], v[96:97] op_sel:[0,1] op_sel_hi:[1,0]
	ds_read2_b32 v[96:97], v104 offset0:34 offset1:35
	s_waitcnt lgkmcnt(1)
	v_pk_add_f32 v[246:247], v[246:247], v[98:99] op_sel:[0,1] op_sel_hi:[1,0]
	ds_read2_b32 v[98:99], v104 offset0:2 offset1:3
	ds_read2_b32 v[102:103], v104 offset0:32 offset1:33
	ds_read2_b32 v[104:105], v104 offset1:1
	s_waitcnt lgkmcnt(3)
	v_pk_add_f32 v[248:249], v[248:249], v[96:97] op_sel:[0,1] op_sel_hi:[1,0]
	s_waitcnt lgkmcnt(2)
	v_pk_add_f32 v[146:147], v[146:147], v[98:99] op_sel:[0,1] op_sel_hi:[1,0]
	s_waitcnt lgkmcnt(1)
	v_pk_add_f32 v[250:251], v[250:251], v[102:103] op_sel:[0,1] op_sel_hi:[1,0]
	s_waitcnt lgkmcnt(0)
	v_pk_add_f32 v[148:149], v[148:149], v[104:105] op_sel:[0,1] op_sel_hi:[1,0]
	s_waitcnt lgkmcnt(0)
	ds_read_b64_tr_b16 v[186:187], v218
	ds_read_b64_tr_b16 v[188:189], v218 offset:512
	ds_read_b64_tr_b16 v[190:191], v218 offset:1024
	ds_read_b64_tr_b16 v[192:193], v218 offset:1536
	ds_read_b64_tr_b16 v[194:195], v218 offset:2048
	ds_read_b64_tr_b16 v[196:197], v218 offset:2560
	ds_read_b64_tr_b16 v[198:199], v218 offset:3072
	ds_read_b64_tr_b16 v[200:201], v218 offset:3584
	ds_read_b64_tr_b16 v[202:203], v218 offset:4096
	ds_read_b64_tr_b16 v[204:205], v218 offset:4608
	ds_read_b64_tr_b16 v[206:207], v218 offset:5120
	ds_read_b64_tr_b16 v[208:209], v218 offset:5632
	ds_read_b64_tr_b16 v[210:211], v218 offset:6144
	ds_read_b64_tr_b16 v[212:213], v218 offset:6656
	ds_read_b64_tr_b16 v[214:215], v218 offset:7168
	ds_read_b64_tr_b16 v[216:217], v218 offset:7680
	v_exp_f32_e32 v236, v236
	v_exp_f32_e32 v134, v134
	v_exp_f32_e32 v237, v237
	v_exp_f32_e32 v135, v135
	v_exp_f32_e32 v238, v238
	v_exp_f32_e32 v136, v136
	v_exp_f32_e32 v239, v239
	v_exp_f32_e32 v137, v137
	v_add_f32_e32 v252, v134, v236
	v_exp_f32_e32 v240, v240
	v_exp_f32_e32 v138, v138
	v_add_f32_e32 v252, 0, v252
	v_add_f32_e32 v253, v135, v237
	v_exp_f32_e32 v241, v241
	v_exp_f32_e32 v139, v139
	v_add_f32_e32 v252, v253, v252
	v_add_f32_e32 v253, v136, v238
	v_exp_f32_e32 v242, v242
	v_exp_f32_e32 v140, v140
	v_add_f32_e32 v252, v253, v252
	v_add_f32_e32 v253, v137, v239
	v_exp_f32_e32 v243, v243
	v_exp_f32_e32 v141, v141
	v_add_f32_e32 v252, v253, v252
	v_add_f32_e32 v253, v138, v240
	v_exp_f32_e32 v244, v244
	v_exp_f32_e32 v142, v142
	v_add_f32_e32 v252, v253, v252
	v_add_f32_e32 v253, v139, v241
	v_exp_f32_e32 v245, v245
	v_exp_f32_e32 v143, v143
	v_add_f32_e32 v252, v253, v252
	v_add_f32_e32 v253, v140, v242
	v_exp_f32_e32 v246, v246
	v_exp_f32_e32 v144, v144
	v_add_f32_e32 v252, v253, v252
	v_add_f32_e32 v253, v141, v243
	v_exp_f32_e32 v247, v247
	v_exp_f32_e32 v145, v145
	v_add_f32_e32 v252, v253, v252
	v_add_f32_e32 v253, v142, v244
	v_exp_f32_e32 v248, v248
	v_exp_f32_e32 v146, v146
	v_add_f32_e32 v252, v253, v252
	v_add_f32_e32 v253, v143, v245
	v_exp_f32_e32 v249, v249
	v_exp_f32_e32 v147, v147
	v_add_f32_e32 v252, v253, v252
	v_add_f32_e32 v253, v144, v246
	v_exp_f32_e32 v250, v250
	v_exp_f32_e32 v148, v148
	v_add_f32_e32 v252, v253, v252
	v_add_f32_e32 v253, v145, v247
	v_exp_f32_e32 v251, v251
	v_exp_f32_e32 v149, v149
	v_add_f32_e32 v252, v253, v252
	v_add_f32_e32 v253, v146, v248
	v_add_f32_e32 v252, v253, v252
	v_add_f32_e32 v253, v147, v249
	v_add_f32_e32 v252, v253, v252
	v_add_f32_e32 v253, v148, v250
	v_add_f32_e32 v252, v253, v252
	v_add_f32_e32 v253, v149, v251
	v_add_f32_e32 v252, v253, v252
	v_add_f32_e32 v131, v131, v252
	v_cvt_pk_bf16_f32 v108, v236, v237
	v_cvt_pk_bf16_f32 v109, v238, v239
	v_cvt_pk_bf16_f32 v110, v240, v241
	v_cvt_pk_bf16_f32 v111, v242, v243
	v_cvt_pk_bf16_f32 v104, v244, v245
	v_cvt_pk_bf16_f32 v105, v246, v247
	v_cvt_pk_bf16_f32 v106, v248, v249
	v_cvt_pk_bf16_f32 v107, v250, v251
	v_cvt_pk_bf16_f32 v100, v134, v135
	v_cvt_pk_bf16_f32 v101, v136, v137
	v_cvt_pk_bf16_f32 v102, v138, v139
	v_cvt_pk_bf16_f32 v103, v140, v141
	v_cvt_pk_bf16_f32 v96, v142, v143
	v_cvt_pk_bf16_f32 v97, v144, v145
	v_cvt_pk_bf16_f32 v98, v146, v147
	v_cvt_pk_bf16_f32 v99, v148, v149
	s_branch .Lmb3_B_tail
